# scan3: drop store-ack waits at chunk-loop back-edge; drop L2 writeback+invalidate of intra-workgroup threadfence between scan directions (workgroup-scope visibility suffices)
# speedup vs baseline: 1.0552x; 1.0552x over previous
; __device__ __forceinline__ void scan_pass3(LAS unsigned char* lds, const Args& a, int l, int it, int tid, int wave, int lane) {
;     ...
;     for (int dir = 0; dir < 2; ++dir) {
;         const ScanCh ch = scan_ch(a, l, dir, h * 64 + 16 * (wave & 3) + (lane & 15));
;         const int s = dir ? nseg - 1 - ts : ts;
;         Raw R; raw_load<true>(R, P, s0, len, dir ? len - 32 - s * SEG : s * SEG, h, dir, dir == 1, tid);
;         scan_load_lora(L, a, l, dir, h, tid);
;     ...
;         __threadfence();
;     }
.LBB0_615:
	s_mov_b32 s24, 1
	s_mov_b64 s[18:19], -1
	s_mov_b64 s[40:41], 0
	s_and_b64 vcc, exec, s[88:89]
	v_readlane_b32 s86, v241, 12
	v_readlane_b32 s89, v241, 13
	s_waitcnt vmcnt(0)
	s_cbranch_vccnz .LBB0_609

; __device__ __forceinline__ unsigned f2bf(float f) { return pk2(f, f) & 0xffffu; }
; __device__ __forceinline__ int mrow(int r, int hi) { return (r & 3) + 8 * (r >> 2) + 4 * hi; }
; template <int NV, bool WITHY> __device__ __forceinline__ void scan_chunk(const ScanLds& L, f32x16& st, bool hasT, int kt, int vt, int wave, int lane_, bf16* ypark = nullptr) {
;     ...
;     if (WITHY && utile >= 0) {
;         mm32<2>(accy, L.Abr, 40, 0, L.Ub, 40, 32 * utile, l31, hi);
;         if (ypark) {
; #pragma unroll
;             for (int r = 0; r < 16; ++r) ypark[(size_t)mrow(r, hi) * 1024 + 32 * utile + l31] = (bf16)f2bf(accy[r]);
; __device__ __forceinline__ void scan_pass3(LAS unsigned char* lds, const Args& a, int l, int it, int tid, int wave, int lane) {
;     ...
;                 scan_chunk<64, true>(L, st, hasT, kt, vt, wave, lane, Y + (size_t)(s0 + pos0) * 1024 + 512 + h * 64);
.LBB0_777:
	s_and_b64 vcc, exec, s[54:55]
	s_waitcnt lgkmcnt(0)
	s_barrier
	s_waitcnt vmcnt(0)
	s_cbranch_vccnz .LBB0_779
	v_readlane_b32 s1, v242, 47
	v_mul_lo_u32 v38, v212, s93
	s_add_i32 s0, s8, s59
	v_add3_u32 v1, s1, v169, v211
	ds_read_b128 v[34:37], v1
	s_add_i32 s1, 0, 0x11400
	v_add3_u32 v46, s1, v38, v211
	ds_read_b128 v[38:41], v46
	ds_read_b128 v[42:45], v1 offset:32
	ds_read_b128 v[46:49], v46 offset:32
	s_ashr_i32 s1, s0, 31
	s_lshl_b64 s[0:1], s[0:1], 11
	s_waitcnt lgkmcnt(2)
	v_mfma_f32_32x32x16_bf16 v[18:33], v[34:37], v[38:41], v[18:33]
	s_add_u32 s0, s6, s0
	s_addc_u32 s1, s7, s1
	v_mov_b32_e32 v177, v0
	v_ashrrev_i32_e32 v175, 31, v174
	v_lshl_add_u64 v[34:35], s[0:1], 0, v[176:177]
	v_lshlrev_b64 v[36:37], 11, v[174:175]
	v_ashrrev_i32_e32 v173, 31, v172
	s_waitcnt lgkmcnt(0)
	v_mfma_f32_32x32x16_bf16 v[18:33], v[42:45], v[46:49], v[18:33]
	v_lshl_add_u64 v[36:37], v[34:35], 0, v[36:37]
	v_lshlrev_b64 v[38:39], 11, v[172:173]
	v_ashrrev_i32_e32 v171, 31, v170
	v_lshl_add_u64 v[38:39], v[34:35], 0, v[38:39]
	v_ashrrev_i32_e32 v169, 31, v168
	s_nop 6
	v_cvt_pk_bf16_f32 v1, v18, s0
	v_cvt_pk_bf16_f32 v18, v19, s0
	global_store_short v[36:37], v1, off offset:1024
	global_store_short v[38:39], v18, off offset:1024
	v_lshlrev_b64 v[18:19], 11, v[170:171]
	v_cvt_pk_bf16_f32 v20, v20, s0
	v_lshl_add_u64 v[18:19], v[34:35], 0, v[18:19]
	global_store_short v[18:19], v20, off offset:1024
	v_lshlrev_b64 v[18:19], 11, v[168:169]
	v_cvt_pk_bf16_f32 v1, v21, s0
	v_lshl_add_u64 v[18:19], v[34:35], 0, v[18:19]
	global_store_short v[18:19], v1, off offset:1024
	v_cvt_pk_bf16_f32 v1, v22, s0
	s_movk_i32 s0, 0x4000
	v_add_co_u32_e32 v18, vcc, s0, v36
	s_nop 1
	v_addc_co_u32_e32 v19, vcc, 0, v37, vcc
	global_store_short v[18:19], v1, off offset:1024
	v_cvt_pk_bf16_f32 v1, v23, s0
	global_store_short v[18:19], v1, off offset:3072
	v_cvt_pk_bf16_f32 v1, v24, s0
	s_movk_i32 s0, 0x5000
	v_add_co_u32_e32 v18, vcc, s0, v36
	s_nop 1
	v_addc_co_u32_e32 v19, vcc, 0, v37, vcc
	global_store_short v[18:19], v1, off offset:1024
	v_cvt_pk_bf16_f32 v1, v25, s0
	global_store_short v[18:19], v1, off offset:3072
	v_cvt_pk_bf16_f32 v1, v26, s0
	s_mov_b32 s0, 0x8000
	v_add_co_u32_e32 v18, vcc, s0, v36
	s_nop 1
	v_addc_co_u32_e32 v19, vcc, 0, v37, vcc
	global_store_short v[18:19], v1, off offset:1024
	v_cvt_pk_bf16_f32 v1, v27, s0
	global_store_short v[18:19], v1, off offset:3072
	v_add_co_u32_e32 v18, vcc, 0x9000, v36
	v_cvt_pk_bf16_f32 v1, v28, s0
	s_nop 0
	v_addc_co_u32_e32 v19, vcc, 0, v37, vcc
	global_store_short v[18:19], v1, off offset:1024
	v_cvt_pk_bf16_f32 v1, v29, s0
	global_store_short v[18:19], v1, off offset:3072
	v_add_co_u32_e32 v18, vcc, 0xc000, v36
	v_cvt_pk_bf16_f32 v1, v30, s0
	s_nop 0
	v_addc_co_u32_e32 v19, vcc, 0, v37, vcc
	global_store_short v[18:19], v1, off offset:1024
	v_cvt_pk_bf16_f32 v1, v31, s0
	global_store_short v[18:19], v1, off offset:3072
	v_add_co_u32_e32 v18, vcc, 0xd000, v36
	v_cvt_pk_bf16_f32 v1, v32, s0
	s_nop 0
	v_addc_co_u32_e32 v19, vcc, 0, v37, vcc
	global_store_short v[18:19], v1, off offset:1024
	v_cvt_pk_bf16_f32 v1, v33, s0
	global_store_short v[18:19], v1, off offset:3072

; __device__ __forceinline__ void scan_pass3(LAS unsigned char* lds, const Args& a, int l, int it, int tid, int wave, int lane) {
;     ...
;                 scan_chunk<64, true>(L, st, hasT, kt, vt, wave, lane, Y + (size_t)(s0 + pos0) * 1024 + 512 + h * 64);
;                 if (tid < 32) SB0[(size_t)(s0 + pos0 + tid) * 8 + h] = L.SBs[tid];
.LBB0_781:
	s_nop 0
	s_nop 10
	v_mov_b64_e32 v[48:49], v[16:17]
	v_mov_b64_e32 v[46:47], v[14:15]
	v_mov_b64_e32 v[44:45], v[12:13]
	v_mov_b64_e32 v[42:43], v[10:11]
	v_mov_b64_e32 v[40:41], v[8:9]
	v_mov_b64_e32 v[38:39], v[6:7]
	v_mov_b64_e32 v[36:37], v[4:5]
	v_mov_b64_e32 v[34:35], v[2:3]
	s_and_saveexec_b64 s[0:1], s[44:45]
	s_cbranch_execz .LBB0_783
	ds_read_b32 v1, v191
	v_add_u32_e32 v2, s8, v97
	v_ashrrev_i32_e32 v3, 31, v2
	v_lshlrev_b64 v[2:3], 5, v[2:3]
	v_lshl_add_u64 v[2:3], s[2:3], 0, v[2:3]
	s_waitcnt lgkmcnt(0)
	global_store_dword v[2:3], v1, off

; __device__ __forceinline__ void scan_pass3(LAS unsigned char* lds, const Args& a, int l, int it, int tid, int wave, int lane) {
;     ...
;         for (int bt = 0; bt < SEG / 32; ++bt) {
;             const int n0 = s * SEG + 32 * bt; const int pos0 = dir ? len - 32 - n0 : n0;
;             const int n1 = n0 + 32; const int pos1 = dir ? len - 32 - n1 : n1;
;             scan_prep<64, true>(L, R, P, mu, s0, len, pos1, bt + 1 < SEG / 32, h, dir, ch, dir == 1, tid, wave, lane);
.LBB0_784:
	s_sub_i32 s19, s19, 32
	s_sub_i32 s58, s58, 32
	s_cmp_eq_u32 s9, s18
	v_add_u32_e32 v97, 32, v97
	s_cbranch_scc1 .LBB0_615
	v_mov_b64_e32 v[2:3], v[34:35]
	s_mov_b32 s59, s60
	v_mov_b64_e32 v[4:5], v[36:37]
	v_mov_b64_e32 v[6:7], v[38:39]
	v_mov_b64_e32 v[8:9], v[40:41]
	v_mov_b64_e32 v[10:11], v[42:43]
	v_mov_b64_e32 v[12:13], v[44:45]
	v_mov_b64_e32 v[14:15], v[46:47]
	v_mov_b64_e32 v[16:17], v[48:49]
	s_branch .LBB0_671

; #define TIDS() int lane_ = (int)__builtin_amdgcn_mbcnt_hi(~0u, __builtin_amdgcn_mbcnt_lo(~0u, 0u)); asm volatile("" : "+v"(lane_)); const int lane = lane_, wave = wave0, tid = wave0 * 64 + lane, gw = blockIdx.x * NWAVES + wave; (void)gw; (void)lane; (void)tid; LOAD_ARGS()
; template <bool COOP>
; __global__ void __launch_bounds__(NTHR, 2) fwd_kernel(Args a0) {
;     ...
;     if (RUN(37)) { TIDS(); final_norm_phase(P_X, a.in[28], gw, NGW, lane); }
;     ...
; }
.LBB0_1229:
	s_endpgm
	.p2align	8
